# conv item inner loop: removed three vmcnt(0) WAW guards that serialized the four loads of each 4-token step (previous step's loads are always fully waited in the token blocks)
# speedup vs baseline: 1.0367x; 1.0022x over previous
; DI void conv_item(int wv, const Params& p, int layer, int it) {
;     ...
;       for (int tb = tstart; tb < tstart + RL; tb += 4) {
;         u32x4 wn[4];
; #pragma unroll
;         for (int u = 0; u < 4; ++u)
;           if (tb + u < tstart + RL) wn[u] = *(const u32x4*)(colp + (long)(tb + u) * 64);
; #pragma unroll
;         for (int u = 0; u < 4; ++u) {
;           const int t = tb + u;
;           if (t < tstart + RL) {
;             const u32x4 w3 = wn[u];
.LBB0_471:
	s_or_b64 exec, exec, s[0:1]
	v_add_u32_e32 v88, 1, v76
	v_cmp_lt_i32_e64 s[6:7], v88, v1
	v_ashrrev_i32_e32 v89, 31, v88
	s_and_saveexec_b64 s[0:1], s[6:7]
	s_cbranch_execz .LBB0_473
	v_lshlrev_b64 v[52:53], 7, v[88:89]
	v_lshl_add_u64 v[52:53], v[78:79], 0, v[52:53]
	global_load_dwordx4 v[52:55], v[52:53], off
.LBB0_473:
	s_or_b64 exec, exec, s[0:1]
	v_add_u32_e32 v86, 2, v76
	v_cmp_lt_i32_e64 s[0:1], v86, v1
	v_ashrrev_i32_e32 v87, 31, v86
	s_and_saveexec_b64 s[16:17], s[0:1]
	s_cbranch_execz .LBB0_475
	v_lshlrev_b64 v[56:57], 7, v[86:87]
	v_lshl_add_u64 v[56:57], v[78:79], 0, v[56:57]
	global_load_dwordx4 v[56:59], v[56:57], off
.LBB0_475:
	s_or_b64 exec, exec, s[16:17]
	v_add_u32_e32 v84, 3, v76
	v_cmp_lt_i32_e32 vcc, v84, v1
	v_ashrrev_i32_e32 v85, 31, v84
	s_and_saveexec_b64 s[16:17], vcc
	s_cbranch_execz .LBB0_477
	v_lshlrev_b64 v[60:61], 7, v[84:85]
	v_lshl_add_u64 v[60:61], v[78:79], 0, v[60:61]
	global_load_dwordx4 v[60:63], v[60:61], off
